# attention steps: K/V staging no longer waits for the previous step output-store acks (vmcnt(0) -> vmcnt(8) at step start, full wait only on loop entry)
# speedup vs baseline: 1.0044x; 1.0044x over previous
; #define ATTN_LOAD_BLK(A, NB) do { _Pragma("unroll") for (int i = 0; i < 4; ++i) { const int idx = tid + 512 * i, row = idx >> 4, ch = idx & 15; \
;             const bf16_t* src = proj + ((A).tb + ((size_t)((NB) * 128 + row) << (A).dl) + (A).r) * DIN + (A).h * 128 + ch * 8; kv[i] = *(const u32x4*)(src + 1024); vv[i] = *(const u32x4*)(src + 2048); } } while (0)
; #define ATTN_STORE_BLK(HH) do { _Pragma("unroll") for (int i = 0; i < 4; ++i) { const int idx = tid + 512 * i, row = idx >> 4, ch = idx & 15; \
;             *(LAS u32x4*)(Kl + (HH) * KH + row * 272 + ch * 16) = kv[i]; *(LAS u32x4*)(Vl + (HH) * VH + row * 288 + ch * 16) = vv[i]; } } while (0)
; #define ATTN_LOAD_Q(A) do { const size_t qt_ = (A).tb + ((size_t)((A).n * 128 + wid * 16 + li) << (A).dl) + (A).r; \
;             _Pragma("unroll") for (int s = 0; s < 4; ++s) qf[s] = *(const bf16x8*)(proj + qt_ * DIN + (A).h * 128 + s * 32 + g * 8); } while (0)
; __device__ __forceinline__ void attn_phase(const Params& p, LAS unsigned char* lds, int l, int mode) {
;     ...
;     for (int wg = blockIdx.x; wg < 256; wg += gridDim.x) {
;         AttnStep cur = attn_step(wg, 0, mode);
;         if (mode && cur.n > 0) { ATTN_LOAD_BLK(cur, cur.n - 1); ATTN_STORE_BLK(1); }
;         ATTN_LOAD_BLK(cur, cur.n); ATTN_LOAD_Q(cur);
.LBB0_230:
	v_add_u32_e32 v0, s43, v143
	v_add_u32_e32 v16, s43, v145
	s_lshl_b64 s[46:47], s[52:53], 1
	v_ashrrev_i32_e32 v1, 31, v0
	v_ashrrev_i32_e32 v17, 31, v16
	v_lshl_add_u64 v[114:115], v[100:101], 0, s[46:47]
	v_lshl_add_u64 v[0:1], s[2:3], 0, v[0:1]
	v_lshl_add_u64 v[16:17], s[2:3], 0, v[16:17]
	v_mad_u64_u32 v[2:3], s[54:55], v0, s59, v[114:115]
	v_add_u32_e32 v0, s43, v144
	v_mad_u64_u32 v[18:19], s[54:55], v16, s59, v[114:115]
	v_add_u32_e32 v16, s43, v146
	v_mad_i32_i24 v3, v1, s59, v3
	v_ashrrev_i32_e32 v1, 31, v0
	v_mad_i32_i24 v19, v17, s59, v19
	v_ashrrev_i32_e32 v17, 31, v16
	v_lshl_add_u64 v[0:1], s[2:3], 0, v[0:1]
	v_lshl_add_u64 v[16:17], s[2:3], 0, v[16:17]
	v_add_co_u32_e32 v8, vcc, 0x1000, v2
	v_mad_u64_u32 v[10:11], s[54:55], v0, s59, v[114:115]
	v_mad_u64_u32 v[26:27], s[54:55], v16, s59, v[114:115]
	v_addc_co_u32_e32 v9, vcc, 0, v3, vcc
	s_movk_i32 s56, 0x1000
	v_add_u32_e32 v32, s43, v141
	v_readlane_b32 s54, v252, 57
	v_mad_i32_i24 v11, v1, s59, v11
	v_add_co_u32_e32 v12, vcc, s56, v10
	v_ashrrev_i32_e32 v33, 31, v32
	v_readlane_b32 s55, v252, 58
	v_addc_co_u32_e32 v13, vcc, 0, v11, vcc
	v_lshl_add_u64 v[32:33], s[2:3], 0, v[32:33]
	v_mov_b64_e32 v[34:35], s[54:55]
	v_add_co_u32_e32 v24, vcc, s56, v18
	v_mad_u64_u32 v[34:35], s[54:55], v32, s59, v[34:35]
	s_nop 0
	v_addc_co_u32_e32 v25, vcc, 0, v19, vcc
	v_mad_i32_i24 v35, v33, s59, v35
	v_mad_i32_i24 v27, v17, s59, v27
	v_add_co_u32_e32 v28, vcc, s56, v26
	v_lshl_add_u64 v[32:33], v[34:35], 0, s[46:47]
	v_lshlrev_b32_e32 v152, 1, v102
	v_addc_co_u32_e32 v29, vcc, 0, v27, vcc
	v_lshl_add_u64 v[32:33], v[32:33], 0, v[152:153]
	global_load_dwordx4 v[0:3], v[2:3], off offset:2048
	s_nop 0
	global_load_dwordx4 v[4:7], v[10:11], off offset:2048
	s_nop 0
	global_load_dwordx4 v[8:11], v[8:9], off
	s_nop 0
	global_load_dwordx4 v[12:15], v[12:13], off
	s_nop 0
	global_load_dwordx4 v[16:19], v[18:19], off offset:2048
	s_nop 0
	global_load_dwordx4 v[20:23], v[26:27], off offset:2048
	s_nop 0
	global_load_dwordx4 v[24:27], v[24:25], off
	s_nop 0
	global_load_dwordx4 v[28:31], v[28:29], off
	s_nop 0
	global_load_dwordx4 v[48:51], v[32:33], off
	global_load_dwordx4 v[88:91], v[32:33], off offset:64
	global_load_dwordx4 v[92:95], v[32:33], off offset:128
	global_load_dwordx4 v[96:99], v[32:33], off offset:192
	s_mov_b32 s43, 0
	v_lshl_add_u64 v[116:117], v[250:251], 0, s[46:47]
	v_lshl_add_u64 v[118:119], v[112:113], 0, s[46:47]
	v_lshl_add_u64 v[120:121], s[52:53], 2, v[236:237]
	s_lshl_b32 s46, s42, 1
	s_mov_b64 vcc, -1
	s_lshl_b32 s52, s42, 2
	s_mov_b32 s42, s33
	s_waitcnt vmcnt(0)
	s_branch .LBB0_232

; #define ATTN_LOAD_BLK(A, NB) do { _Pragma("unroll") for (int i = 0; i < 4; ++i) { const int idx = tid + 512 * i, row = idx >> 4, ch = idx & 15; \
;             const bf16_t* src = proj + ((A).tb + ((size_t)((NB) * 128 + row) << (A).dl) + (A).r) * DIN + (A).h * 128 + ch * 8; kv[i] = *(const u32x4*)(src + 1024); vv[i] = *(const u32x4*)(src + 2048); } } while (0)
; #define ATTN_STORE_BLK(HH) do { _Pragma("unroll") for (int i = 0; i < 4; ++i) { const int idx = tid + 512 * i, row = idx >> 4, ch = idx & 15; \
;             *(LAS u32x4*)(Kl + (HH) * KH + row * 272 + ch * 16) = kv[i]; *(LAS u32x4*)(Vl + (HH) * VH + row * 288 + ch * 16) = vv[i]; } } while (0)
; #define ATTN_LOAD_Q(A) do { const size_t qt_ = (A).tb + ((size_t)((A).n * 128 + wid * 16 + li) << (A).dl) + (A).r; \
;             _Pragma("unroll") for (int s = 0; s < 4; ++s) qf[s] = *(const bf16x8*)(proj + qt_ * DIN + (A).h * 128 + s * 32 + g * 8); } while (0)
; __device__ __forceinline__ void attn_phase(const Params& p, LAS unsigned char* lds, int l, int mode) {
;     ...
;             ATTN_STORE_BLK(c);
;             bf16x8 qc[4];
; #pragma unroll
;             for (int s = 0; s < 4; ++s) qc[s] = qf[s];
;             asm volatile("s_waitcnt lgkmcnt(0)" ::: "memory"); __builtin_amdgcn_s_barrier(); asm volatile("" ::: "memory");
;             AttnStep nxt = attn_step(wg, (q + 1 < nsteps) ? q + 1 : q, mode);
;             if (q + 1 < nsteps) { ATTN_LOAD_BLK(nxt, nxt.n); ATTN_LOAD_Q(nxt); }
.LBB0_234:
	s_mul_i32 s56, s57, 0x8800
	v_add_u32_e32 v32, s56, v137
	s_mul_i32 s55, s57, 0x9000
	v_add_u32_e32 v33, s55, v142
	v_add_u32_e32 v34, v32, v147
	s_waitcnt vmcnt(8)
	ds_write_b128 v34, v[0:3]
	v_add_u32_e32 v34, v33, v148
	ds_write_b128 v34, v[8:11]
	v_add_u32_e32 v34, v32, v149
	ds_write_b128 v34, v[4:7]
	v_add_u32_e32 v34, v33, v150
	ds_write_b128 v34, v[12:15]
	v_add_u32_e32 v34, v32, v151
	ds_write_b128 v34, v[16:19]
	v_add_u32_e32 v34, v33, v156
	v_add_u32_e32 v32, v32, v157
	ds_write_b128 v34, v[24:27]
	ds_write_b128 v32, v[20:23]
	v_add_u32_e32 v32, v33, v158
	s_add_i32 s47, s43, 1
	ds_write_b128 v32, v[28:31]
	s_cmp_lt_u32 s43, 3
	s_waitcnt lgkmcnt(0)
	s_barrier
	s_cselect_b32 s54, s47, s43
	s_add_i32 s54, s54, s33
	v_mov_b64_e32 v[32:33], v[48:49]
	v_mov_b64_e32 v[36:37], v[88:89]
	v_mov_b64_e32 v[40:41], v[92:93]
	v_mov_b64_e32 v[44:45], v[96:97]
	s_cmp_gt_u32 s43, 2
	v_mov_b64_e32 v[34:35], v[50:51]
	v_mov_b64_e32 v[38:39], v[90:91]
	v_mov_b64_e32 v[42:43], v[94:95]
	v_mov_b64_e32 v[46:47], v[98:99]
	s_cbranch_scc1 .LBB0_231
	s_lshl_b32 s43, s54, 7
	v_add_u32_e32 v0, s43, v143
	v_ashrrev_i32_e32 v1, 31, v0
	v_lshl_add_u64 v[0:1], s[2:3], 0, v[0:1]
	v_mad_u64_u32 v[2:3], vcc, v0, s59, v[114:115]
	v_add_u32_e32 v0, s43, v144
	v_mad_i32_i24 v3, v1, s59, v3
	v_ashrrev_i32_e32 v1, 31, v0
	v_add_co_u32_e32 v8, vcc, 0x1000, v2
	v_lshl_add_u64 v[0:1], s[2:3], 0, v[0:1]
	v_add_u32_e32 v16, s43, v145
	v_addc_co_u32_e32 v9, vcc, 0, v3, vcc
	v_mad_u64_u32 v[10:11], vcc, v0, s59, v[114:115]
	s_movk_i32 s58, 0x1000
	v_ashrrev_i32_e32 v17, 31, v16
	v_mad_i32_i24 v11, v1, s59, v11
	v_add_co_u32_e32 v12, vcc, s58, v10
	v_lshl_add_u64 v[16:17], s[2:3], 0, v[16:17]
	s_nop 0
	v_addc_co_u32_e32 v13, vcc, 0, v11, vcc
	v_mad_u64_u32 v[18:19], vcc, v16, s59, v[114:115]
	v_add_u32_e32 v16, s43, v146
	v_mad_i32_i24 v19, v17, s59, v19
	v_ashrrev_i32_e32 v17, 31, v16
	v_add_co_u32_e32 v24, vcc, s58, v18
	v_lshl_add_u64 v[16:17], s[2:3], 0, v[16:17]
	v_add_u32_e32 v32, s43, v141
	v_addc_co_u32_e32 v25, vcc, 0, v19, vcc
	v_mad_u64_u32 v[26:27], vcc, v16, s59, v[114:115]
	v_ashrrev_i32_e32 v33, 31, v32
	v_mad_i32_i24 v27, v17, s59, v27
	v_add_co_u32_e32 v28, vcc, s58, v26
	v_lshl_add_u64 v[32:33], s[2:3], 0, v[32:33]
	s_nop 0
	v_addc_co_u32_e32 v29, vcc, 0, v27, vcc
	v_mad_u64_u32 v[44:45], vcc, v32, s59, v[116:117]
	v_mad_i32_i24 v45, v33, s59, v45
	global_load_dwordx4 v[0:3], v[2:3], off offset:2048
	s_nop 0
	global_load_dwordx4 v[4:7], v[10:11], off offset:2048
	s_nop 0
	global_load_dwordx4 v[8:11], v[8:9], off
	s_nop 0
	global_load_dwordx4 v[12:15], v[12:13], off
	s_nop 0
	global_load_dwordx4 v[16:19], v[18:19], off offset:2048
	s_nop 0
	global_load_dwordx4 v[20:23], v[26:27], off offset:2048
	s_nop 0
	global_load_dwordx4 v[24:27], v[24:25], off
	s_nop 0
	global_load_dwordx4 v[28:31], v[28:29], off
	s_nop 0
	global_load_dwordx4 v[32:35], v[44:45], off
	global_load_dwordx4 v[36:39], v[44:45], off offset:64
	global_load_dwordx4 v[40:43], v[44:45], off offset:128
	s_nop 0
	global_load_dwordx4 v[44:47], v[44:45], off offset:192
	s_branch .LBB0_231

; #define ATTN_LOAD_BLK(A, NB) do { _Pragma("unroll") for (int i = 0; i < 4; ++i) { const int idx = tid + 512 * i, row = idx >> 4, ch = idx & 15; \
;             const bf16_t* src = proj + ((A).tb + ((size_t)((NB) * 128 + row) << (A).dl) + (A).r) * DIN + (A).h * 128 + ch * 8; kv[i] = *(const u32x4*)(src + 1024); vv[i] = *(const u32x4*)(src + 2048); } } while (0)
; #define ATTN_STORE_BLK(HH) do { _Pragma("unroll") for (int i = 0; i < 4; ++i) { const int idx = tid + 512 * i, row = idx >> 4, ch = idx & 15; \
;             *(LAS u32x4*)(Kl + (HH) * KH + row * 272 + ch * 16) = kv[i]; *(LAS u32x4*)(Vl + (HH) * VH + row * 288 + ch * 16) = vv[i]; } } while (0)
; #define ATTN_LOAD_Q(A) do { const size_t qt_ = (A).tb + ((size_t)((A).n * 128 + wid * 16 + li) << (A).dl) + (A).r; \
;             _Pragma("unroll") for (int s = 0; s < 4; ++s) qf[s] = *(const bf16x8*)(proj + qt_ * DIN + (A).h * 128 + s * 32 + g * 8); } while (0)
; __device__ __forceinline__ void attn_phase(const Params& p, LAS unsigned char* lds, int l, int mode) {
;     ...
;     for (int wg = blockIdx.x; wg < 256; wg += gridDim.x) {
;         AttnStep cur = attn_step(wg, 0, mode);
;         if (mode && cur.n > 0) { ATTN_LOAD_BLK(cur, cur.n - 1); ATTN_STORE_BLK(1); }
;         ATTN_LOAD_BLK(cur, cur.n); ATTN_LOAD_Q(cur);
.LBB0_302:
	s_ashr_i32 s13, s12, 31
	s_lshl_b64 s[20:21], s[12:13], 12
	s_and_b32 s12, s22, 7
	s_or_b32 s22, s20, s35
	s_mov_b32 s23, s21
	s_lshl_b32 s52, s12, 8
	v_lshlrev_b64 v[0:1], s30, v[106:107]
	v_lshl_add_u64 v[16:17], v[100:101], 0, s[52:53]
	v_lshl_add_u64 v[0:1], s[22:23], 0, v[0:1]
	s_movk_i32 s26, 0x3000
	v_lshlrev_b64 v[18:19], s30, v[110:111]
	v_mad_u64_u32 v[2:3], s[24:25], v0, s26, v[16:17]
	v_lshl_add_u64 v[18:19], s[22:23], 0, v[18:19]
	v_mad_i32_i24 v3, v1, s26, v3
	s_movk_i32 s13, 0x1000
	v_lshlrev_b64 v[0:1], s30, v[108:109]
	v_mad_u64_u32 v[20:21], s[24:25], v18, s26, v[16:17]
	v_add_co_u32_e32 v8, vcc, s13, v2
	v_lshl_add_u64 v[0:1], s[22:23], 0, v[0:1]
	v_mad_i32_i24 v21, v19, s26, v21
	v_lshlrev_b64 v[18:19], s30, v[112:113]
	v_lshlrev_b64 v[32:33], s30, v[102:103]
	v_addc_co_u32_e32 v9, vcc, 0, v3, vcc
	v_mad_u64_u32 v[10:11], s[24:25], v0, s26, v[16:17]
	v_lshl_add_u64 v[18:19], s[22:23], 0, v[18:19]
	v_lshl_add_u64 v[32:33], s[22:23], 0, v[32:33]
	v_readlane_b32 s22, v252, 57
	v_mad_i32_i24 v11, v1, s26, v11
	v_add_co_u32_e32 v12, vcc, s13, v10
	v_readlane_b32 s23, v252, 58
	s_nop 0
	v_addc_co_u32_e32 v13, vcc, 0, v11, vcc
	v_mov_b64_e32 v[34:35], s[22:23]
	v_add_co_u32_e32 v24, vcc, s13, v20
	v_mad_u64_u32 v[34:35], s[22:23], v32, s26, v[34:35]
	s_nop 0
	v_addc_co_u32_e32 v25, vcc, 0, v21, vcc
	v_mad_u64_u32 v[26:27], s[24:25], v18, s26, v[16:17]
	v_mad_i32_i24 v35, v33, s26, v35
	v_mad_i32_i24 v27, v19, s26, v27
	v_add_co_u32_e32 v28, vcc, s13, v26
	v_lshl_add_u64 v[32:33], v[34:35], 0, s[52:53]
	v_lshlrev_b32_e32 v118, 1, v104
	v_mov_b32_e32 v119, v153
	v_addc_co_u32_e32 v29, vcc, 0, v27, vcc
	v_lshl_add_u64 v[32:33], v[32:33], 0, v[118:119]
	global_load_dwordx4 v[0:3], v[2:3], off offset:2048
	s_nop 0
	global_load_dwordx4 v[4:7], v[10:11], off offset:2048
	s_nop 0
	global_load_dwordx4 v[8:11], v[8:9], off
	s_nop 0
	global_load_dwordx4 v[12:15], v[12:13], off
	s_nop 0
	global_load_dwordx4 v[16:19], v[20:21], off offset:2048
	s_nop 0
	global_load_dwordx4 v[20:23], v[26:27], off offset:2048
	s_nop 0
	global_load_dwordx4 v[24:27], v[24:25], off
	s_nop 0
	global_load_dwordx4 v[28:31], v[28:29], off
	s_nop 0
	global_load_dwordx4 v[48:51], v[32:33], off
	global_load_dwordx4 v[84:87], v[32:33], off offset:64
	global_load_dwordx4 v[88:91], v[32:33], off offset:128
	global_load_dwordx4 v[92:95], v[32:33], off offset:192
	s_mov_b32 s37, 0
	s_mov_b32 s33, 1
	s_mov_b32 s22, 0
	s_waitcnt vmcnt(0)
	s_branch .LBB0_304

; #define ATTN_STORE_BLK(HH) do { _Pragma("unroll") for (int i = 0; i < 4; ++i) { const int idx = tid + 512 * i, row = idx >> 4, ch = idx & 15; \
;             *(LAS u32x4*)(Kl + (HH) * KH + row * 272 + ch * 16) = kv[i]; *(LAS u32x4*)(Vl + (HH) * VH + row * 288 + ch * 16) = vv[i]; } } while (0)
; __device__ __forceinline__ AttnStep attn_step(int wg, int q, int mode) {
;     ...
;     if (mode) { const int bh = wg >> 3; a.tb = (size_t)(bh >> 3) * SEQ; a.h = bh & 7; a.br = 0; a.dl = 0; a.r = 0; a.n = 4 * (wg & 7) + q; a.first = (q == 0); }
;     else if (wg < 128) { a.tb = (size_t)(wg >> 5) * SEQ; a.h = (wg >> 2) & 7; a.br = 1; a.dl = 2; a.r = wg & 3; a.n = q; a.first = (q == 0); }
;     else { const int c16 = (wg - 128) * 4 + (q >> 1); a.tb = (size_t)(c16 >> 7) * SEQ; a.h = (c16 >> 4) & 7; a.br = 2; a.dl = 4; a.r = c16 & 15; a.n = q & 1; a.first = !(q & 1); }
;     return a;
; __device__ __forceinline__ void attn_phase(const Params& p, LAS unsigned char* lds, int l, int mode) {
;     ...
;             ATTN_STORE_BLK(c);
;             bf16x8 qc[4];
; #pragma unroll
;             for (int s = 0; s < 4; ++s) qc[s] = qf[s];
;             asm volatile("s_waitcnt lgkmcnt(0)" ::: "memory"); __builtin_amdgcn_s_barrier(); asm volatile("" ::: "memory");
;             AttnStep nxt = attn_step(wg, (q + 1 < nsteps) ? q + 1 : q, mode);
.LBB0_306:
	s_mul_i32 s38, s39, 0x8800
	v_add_u32_e32 v32, s38, v105
	s_mul_i32 s13, s39, 0x9000
	v_add_u32_e32 v33, s13, v120
	v_add_u32_e32 v34, v32, v121
	s_waitcnt vmcnt(8)
	ds_write_b128 v34, v[0:3]
	v_add_u32_e32 v34, v33, v122
	ds_write_b128 v34, v[8:11]
	v_add_u32_e32 v34, v32, v123
	ds_write_b128 v34, v[4:7]
	v_add_u32_e32 v34, v33, v124
	ds_write_b128 v34, v[12:15]
	v_add_u32_e32 v34, v32, v125
	ds_write_b128 v34, v[16:19]
	v_add_u32_e32 v34, v33, v126
	v_add_u32_e32 v32, v32, v127
	ds_write_b128 v34, v[24:27]
	ds_write_b128 v32, v[20:23]
	v_add_u32_e32 v32, v33, v128
	s_add_i32 s28, s22, 1
	ds_write_b128 v32, v[28:31]
	s_cmp_lt_u32 s22, 7
	s_waitcnt lgkmcnt(0)
	s_barrier
	s_cselect_b64 s[26:27], -1, 0
	s_and_b64 s[24:25], s[26:27], exec
	s_cselect_b32 s29, s28, s22
	s_andn2_b64 vcc, exec, s[8:9]
	s_cbranch_vccnz .LBB0_308
	s_lshr_b32 s22, s29, 1
	v_readlane_b32 s0, v255, 6
	s_add_i32 s22, s0, s22
	s_and_b32 s29, s29, 1
	s_ashr_i32 s24, s22, 7
	s_mov_b32 s36, 4
	s_lshr_b32 s34, s22, 4
	s_and_b32 s31, s22, 15
	s_xor_b32 s33, s29, 1
	s_mov_b64 s[22:23], 0x8000
	s_branch .LBB0_309
